# MLA loop body regenerated: QK(u1) MFMAs under the max/exp/sum VALU of query group 0 and P0*V MFMAs under that of group 1; all 12 K fragments read once per sub-tile; no setprio flips
# baseline (speedup 1.0000x reference)
.LBB0_556:
	s_addk_i32 s4, 0x80
	s_cmpk_lg_i32 s4, 0x1100
	s_waitcnt lgkmcnt(0)
	s_barrier
	s_cbranch_scc0 .LBB0_554

.LBB0_559:
	s_and_b32 s5, s4, 0x80
	v_or_b32_e32 v201, s5, v125
	v_mad_u32_u24 v201, v201, s12, v0
	v_or_b32_e32 v200, s5, v132
	v_mul_u32_u24_e32 v200, 0x48, v200
	v_lshl_add_u32 v200, v200, 1, v130
	ds_read_b128 v[164:167], v201 offset:0
	ds_read_b128 v[168:171], v201 offset:64
	ds_read_b128 v[172:175], v201 offset:128
	ds_read_b128 v[176:179], v201 offset:3328
	ds_read_b128 v[180:183], v201 offset:3392
	ds_read_b128 v[184:187], v201 offset:3456
	ds_read_b128 v[232:235], v201 offset:6656
	ds_read_b128 v[236:239], v201 offset:6720
	ds_read_b128 v[240:243], v201 offset:6784
	ds_read_b128 v[244:247], v201 offset:9984
	ds_read_b128 v[142:145], v201 offset:10048
	ds_read_b128 v[146:149], v201 offset:10112
	s_waitcnt lgkmcnt(11)
	v_mfma_f32_16x16x32_bf16 v[78:81], v[164:167], v[2:5], 0
	s_waitcnt lgkmcnt(10)
	v_mfma_f32_16x16x32_bf16 v[78:81], v[168:171], v[6:9], v[78:81]
	s_waitcnt lgkmcnt(9)
	v_mfma_f32_16x16x32_bf16 v[78:81], v[172:175], v[38:41], v[78:81]
	s_waitcnt lgkmcnt(8)
	v_mfma_f32_16x16x32_bf16 v[82:85], v[176:179], v[2:5], 0
	s_waitcnt lgkmcnt(7)
	v_mfma_f32_16x16x32_bf16 v[82:85], v[180:183], v[6:9], v[82:85]
	s_waitcnt lgkmcnt(6)
	v_mfma_f32_16x16x32_bf16 v[82:85], v[184:187], v[38:41], v[82:85]
	s_waitcnt lgkmcnt(5)
	v_mfma_f32_16x16x32_bf16 v[86:89], v[232:235], v[2:5], 0
	s_waitcnt lgkmcnt(4)
	v_mfma_f32_16x16x32_bf16 v[86:89], v[236:239], v[6:9], v[86:89]
	s_waitcnt lgkmcnt(3)
	v_mfma_f32_16x16x32_bf16 v[86:89], v[240:243], v[38:41], v[86:89]
	s_waitcnt lgkmcnt(2)
	v_mfma_f32_16x16x32_bf16 v[90:93], v[244:247], v[2:5], 0
	s_waitcnt lgkmcnt(1)
	v_mfma_f32_16x16x32_bf16 v[90:93], v[142:145], v[6:9], v[90:93]
	s_waitcnt lgkmcnt(0)
	v_mfma_f32_16x16x32_bf16 v[90:93], v[146:149], v[38:41], v[90:93]
	v_mfma_f32_16x16x32_bf16 v[94:97], v[164:167], v[26:29], 0
	v_max3_f32 v150, v78, s18, v79
	v_max3_f32 v150, v150, v80, v81
	v_max3_f32 v150, v150, v82, v83
	v_max3_f32 v150, v150, v84, v85
	v_max3_f32 v150, v150, v86, v87
	v_max3_f32 v150, v150, v88, v89
	s_nop 0
	v_max3_f32 v150, v150, v90, v91
	v_mfma_f32_16x16x32_bf16 v[94:97], v[168:171], v[30:33], v[94:97]
	v_max3_f32 v150, v150, v92, v93
	v_mul_f32_e32 v150, 0x3e16c740, v150
	v_mov_b32_e32 v152, v150
	s_nop 1
	v_permlane16_swap_b32_e32 v152, v150
	v_max_f32_e32 v150, v150, v152
	v_mov_b32_e32 v152, v150
	s_nop 1
	v_permlane32_swap_b32_e32 v152, v150
	v_mfma_f32_16x16x32_bf16 v[94:97], v[172:175], v[42:45], v[94:97]
	v_max_f32_e32 v150, v150, v152
	v_add_f32_e32 v154, 0x41000000, v139
	v_cmp_gt_f32_e32 vcc, v150, v154
	s_cbranch_vccz .Lmla_s0_keep0
	v_max_f32_e32 v158, v139, v150
	v_sub_f32_e32 v154, v139, v158
	v_exp_f32_e32 v154, v154
	v_mov_b32_e32 v139, v158
	v_mul_f32_e32 v141, v141, v154
	v_pk_mul_f32 v[74:75], v[74:75], v[154:155] op_sel_hi:[1,0]
	v_pk_mul_f32 v[76:77], v[76:77], v[154:155] op_sel_hi:[1,0]
	v_pk_mul_f32 v[70:71], v[70:71], v[154:155] op_sel_hi:[1,0]
	v_pk_mul_f32 v[72:73], v[72:73], v[154:155] op_sel_hi:[1,0]
	v_pk_mul_f32 v[66:67], v[66:67], v[154:155] op_sel_hi:[1,0]
	v_pk_mul_f32 v[68:69], v[68:69], v[154:155] op_sel_hi:[1,0]
	v_pk_mul_f32 v[62:63], v[62:63], v[154:155] op_sel_hi:[1,0]
	v_pk_mul_f32 v[64:65], v[64:65], v[154:155] op_sel_hi:[1,0]
.Lmla_s0_keep0:
	v_fma_f32 v78, v78, s21, -v139
	v_fma_f32 v79, v79, s21, -v139
	v_exp_f32_e32 v78, v78
	v_fma_f32 v80, v80, s21, -v139
	v_exp_f32_e32 v79, v79
	v_mfma_f32_16x16x32_bf16 v[98:101], v[176:179], v[26:29], 0
	v_fma_f32 v81, v81, s21, -v139
	v_exp_f32_e32 v80, v80
	v_exp_f32_e32 v81, v81
	v_fma_f32 v82, v82, s21, -v139
	v_fma_f32 v83, v83, s21, -v139
	v_exp_f32_e32 v82, v82
	v_fma_f32 v84, v84, s21, -v139
	v_mfma_f32_16x16x32_bf16 v[98:101], v[180:183], v[30:33], v[98:101]
	v_exp_f32_e32 v83, v83
	v_fma_f32 v85, v85, s21, -v139
	v_exp_f32_e32 v84, v84
	v_exp_f32_e32 v85, v85
	v_add_f32_e32 v160, 0, v78
	v_add_f32_e32 v160, v79, v160
	v_add_f32_e32 v160, v80, v160
	v_mfma_f32_16x16x32_bf16 v[98:101], v[184:187], v[42:45], v[98:101]
	v_add_f32_e32 v160, v81, v160
	v_cvt_pk_bf16_f32 v78, v78, v79
	v_cvt_pk_bf16_f32 v79, v80, v81
	v_fma_f32 v86, v86, s21, -v139
	v_fma_f32 v87, v87, s21, -v139
	v_exp_f32_e32 v86, v86
	v_fma_f32 v88, v88, s21, -v139
	v_mfma_f32_16x16x32_bf16 v[102:105], v[232:235], v[26:29], 0
	v_exp_f32_e32 v87, v87
	v_fma_f32 v89, v89, s21, -v139
	v_exp_f32_e32 v88, v88
	v_exp_f32_e32 v89, v89
	v_add_f32_e32 v160, v82, v160
	v_add_f32_e32 v160, v83, v160
	v_add_f32_e32 v160, v84, v160
	v_mfma_f32_16x16x32_bf16 v[102:105], v[236:239], v[30:33], v[102:105]
	v_add_f32_e32 v160, v85, v160
	v_cvt_pk_bf16_f32 v80, v82, v83
	v_cvt_pk_bf16_f32 v81, v84, v85
	v_fma_f32 v90, v90, s21, -v139
	v_fma_f32 v91, v91, s21, -v139
	v_exp_f32_e32 v90, v90
	v_fma_f32 v92, v92, s21, -v139
	v_mfma_f32_16x16x32_bf16 v[102:105], v[240:243], v[42:45], v[102:105]
	v_exp_f32_e32 v91, v91
	v_fma_f32 v93, v93, s21, -v139
	v_exp_f32_e32 v92, v92
	v_exp_f32_e32 v93, v93
	v_add_f32_e32 v160, v86, v160
	v_add_f32_e32 v160, v87, v160
	v_add_f32_e32 v160, v88, v160
	v_mfma_f32_16x16x32_bf16 v[106:109], v[244:247], v[26:29], 0
	v_add_f32_e32 v160, v89, v160
	v_cvt_pk_bf16_f32 v82, v86, v87
	v_cvt_pk_bf16_f32 v83, v88, v89
	v_add_f32_e32 v160, v90, v160
	v_add_f32_e32 v160, v91, v160
	v_add_f32_e32 v160, v92, v160
	v_add_f32_e32 v160, v93, v160
	v_mfma_f32_16x16x32_bf16 v[106:109], v[142:145], v[30:33], v[106:109]
	v_cvt_pk_bf16_f32 v84, v90, v91
	v_cvt_pk_bf16_f32 v85, v92, v93
	v_add_f32_e32 v141, v141, v160
	v_mfma_f32_16x16x32_bf16 v[106:109], v[146:149], v[42:45], v[106:109]
	s_waitcnt lgkmcnt(0)
	ds_read_b64_tr_b16 v[164:165], v200 offset:53248
	ds_read_b64_tr_b16 v[166:167], v200 offset:55552
	ds_read_b64_tr_b16 v[168:169], v200 offset:53280
	ds_read_b64_tr_b16 v[170:171], v200 offset:55584
	ds_read_b64_tr_b16 v[172:173], v200 offset:57856
	ds_read_b64_tr_b16 v[174:175], v200 offset:60160
	ds_read_b64_tr_b16 v[176:177], v200 offset:57888
	ds_read_b64_tr_b16 v[178:179], v200 offset:60192
	v_max3_f32 v151, v94, s18, v95
	v_max3_f32 v151, v151, v96, v97
	v_max3_f32 v151, v151, v98, v99
	v_max3_f32 v151, v151, v100, v101
	v_max3_f32 v151, v151, v102, v103
	v_max3_f32 v151, v151, v104, v105
	v_max3_f32 v151, v151, v106, v107
	v_max3_f32 v151, v151, v108, v109
	v_mul_f32_e32 v151, 0x3e16c740, v151
	v_mov_b32_e32 v153, v151
	s_nop 1
	v_permlane16_swap_b32_e32 v153, v151
	v_max_f32_e32 v151, v151, v153
	v_mov_b32_e32 v153, v151
	s_nop 1
	v_permlane32_swap_b32_e32 v153, v151
	v_max_f32_e32 v151, v151, v153
	s_waitcnt lgkmcnt(6)
	ds_read_b64_tr_b16 v[232:233], v200 offset:53312
	ds_read_b64_tr_b16 v[234:235], v200 offset:55616
	ds_read_b64_tr_b16 v[236:237], v200 offset:53344
	ds_read_b64_tr_b16 v[238:239], v200 offset:55648
	ds_read_b64_tr_b16 v[240:241], v200 offset:57920
	ds_read_b64_tr_b16 v[242:243], v200 offset:60224
	ds_read_b64_tr_b16 v[244:245], v200 offset:57952
	ds_read_b64_tr_b16 v[246:247], v200 offset:60256
	v_mfma_f32_16x16x32_bf16 v[74:77], v[164:167], v[78:81], v[74:77]
	v_add_f32_e32 v156, 0x41000000, v138
	v_cmp_gt_f32_e32 vcc, v151, v156
	s_cbranch_vccz .Lmla_s0_keep1
	v_max_f32_e32 v159, v138, v151
	v_sub_f32_e32 v156, v138, v159
	v_exp_f32_e32 v156, v156
	v_mov_b32_e32 v138, v159
	v_mul_f32_e32 v140, v140, v156
	v_pk_mul_f32 v[58:59], v[58:59], v[156:157] op_sel_hi:[1,0]
	v_pk_mul_f32 v[60:61], v[60:61], v[156:157] op_sel_hi:[1,0]
	v_pk_mul_f32 v[54:55], v[54:55], v[156:157] op_sel_hi:[1,0]
	v_pk_mul_f32 v[56:57], v[56:57], v[156:157] op_sel_hi:[1,0]
	v_pk_mul_f32 v[50:51], v[50:51], v[156:157] op_sel_hi:[1,0]
	v_pk_mul_f32 v[52:53], v[52:53], v[156:157] op_sel_hi:[1,0]
	v_pk_mul_f32 v[46:47], v[46:47], v[156:157] op_sel_hi:[1,0]
	v_pk_mul_f32 v[48:49], v[48:49], v[156:157] op_sel_hi:[1,0]
.Lmla_s0_keep1:
	v_fma_f32 v94, v94, s21, -v138
	v_fma_f32 v95, v95, s21, -v138
	v_exp_f32_e32 v94, v94
	v_fma_f32 v96, v96, s21, -v138
	v_exp_f32_e32 v95, v95
	v_fma_f32 v97, v97, s21, -v138
	v_exp_f32_e32 v96, v96
	s_waitcnt lgkmcnt(12)
	v_mfma_f32_16x16x32_bf16 v[70:73], v[168:171], v[78:81], v[70:73]
	v_exp_f32_e32 v97, v97
	v_fma_f32 v98, v98, s21, -v138
	v_fma_f32 v99, v99, s21, -v138
	v_exp_f32_e32 v98, v98
	v_fma_f32 v100, v100, s21, -v138
	v_exp_f32_e32 v99, v99
	v_fma_f32 v101, v101, s21, -v138
	v_exp_f32_e32 v100, v100
	s_waitcnt lgkmcnt(10)
	v_mfma_f32_16x16x32_bf16 v[74:77], v[172:175], v[82:85], v[74:77]
	v_exp_f32_e32 v101, v101
	v_add_f32_e32 v161, 0, v94
	v_add_f32_e32 v161, v95, v161
	v_add_f32_e32 v161, v96, v161
	v_add_f32_e32 v161, v97, v161
	v_cvt_pk_bf16_f32 v94, v94, v95
	v_cvt_pk_bf16_f32 v95, v96, v97
	v_fma_f32 v102, v102, s21, -v138
	s_waitcnt lgkmcnt(8)
	v_mfma_f32_16x16x32_bf16 v[70:73], v[176:179], v[82:85], v[70:73]
	v_fma_f32 v103, v103, s21, -v138
	v_exp_f32_e32 v102, v102
	v_fma_f32 v104, v104, s21, -v138
	v_exp_f32_e32 v103, v103
	v_fma_f32 v105, v105, s21, -v138
	v_exp_f32_e32 v104, v104
	v_exp_f32_e32 v105, v105
	v_add_f32_e32 v161, v98, v161
	s_waitcnt lgkmcnt(6)
	v_mfma_f32_16x16x32_bf16 v[66:69], v[232:235], v[78:81], v[66:69]
	v_add_f32_e32 v161, v99, v161
	v_add_f32_e32 v161, v100, v161
	v_add_f32_e32 v161, v101, v161
	v_cvt_pk_bf16_f32 v96, v98, v99
	v_cvt_pk_bf16_f32 v97, v100, v101
	v_fma_f32 v106, v106, s21, -v138
	v_fma_f32 v107, v107, s21, -v138
	v_exp_f32_e32 v106, v106
	s_waitcnt lgkmcnt(4)
	v_mfma_f32_16x16x32_bf16 v[62:65], v[236:239], v[78:81], v[62:65]
	v_fma_f32 v108, v108, s21, -v138
	v_exp_f32_e32 v107, v107
	v_fma_f32 v109, v109, s21, -v138
	v_exp_f32_e32 v108, v108
	v_exp_f32_e32 v109, v109
	v_add_f32_e32 v161, v102, v161
	v_add_f32_e32 v161, v103, v161
	v_add_f32_e32 v161, v104, v161
	s_waitcnt lgkmcnt(2)
	v_mfma_f32_16x16x32_bf16 v[66:69], v[240:243], v[82:85], v[66:69]
	v_add_f32_e32 v161, v105, v161
	v_cvt_pk_bf16_f32 v98, v102, v103
	v_cvt_pk_bf16_f32 v99, v104, v105
	v_add_f32_e32 v161, v106, v161
	v_add_f32_e32 v161, v107, v161
	v_add_f32_e32 v161, v108, v161
	v_add_f32_e32 v161, v109, v161
	v_cvt_pk_bf16_f32 v100, v106, v107
	s_waitcnt lgkmcnt(0)
	v_mfma_f32_16x16x32_bf16 v[62:65], v[244:247], v[82:85], v[62:65]
	v_cvt_pk_bf16_f32 v101, v108, v109
	v_add_f32_e32 v140, v140, v161
	v_mfma_f32_16x16x32_bf16 v[58:61], v[164:167], v[94:97], v[58:61]
	v_mfma_f32_16x16x32_bf16 v[54:57], v[168:171], v[94:97], v[54:57]
	v_mfma_f32_16x16x32_bf16 v[58:61], v[172:175], v[98:101], v[58:61]
	v_mfma_f32_16x16x32_bf16 v[54:57], v[176:179], v[98:101], v[54:57]
	v_mfma_f32_16x16x32_bf16 v[50:53], v[232:235], v[94:97], v[50:53]
	v_mfma_f32_16x16x32_bf16 v[46:49], v[236:239], v[94:97], v[46:49]
	v_mfma_f32_16x16x32_bf16 v[50:53], v[240:243], v[98:101], v[50:53]
	v_mfma_f32_16x16x32_bf16 v[46:49], v[244:247], v[98:101], v[46:49]
	v_add_u32_e32 v200, 0x2400, v200
	ds_read_b128 v[164:167], v201 offset:13312
	ds_read_b128 v[168:171], v201 offset:13376
	ds_read_b128 v[172:175], v201 offset:13440
	ds_read_b128 v[176:179], v201 offset:16640
	ds_read_b128 v[180:183], v201 offset:16704
	ds_read_b128 v[184:187], v201 offset:16768
	ds_read_b128 v[232:235], v201 offset:19968
	ds_read_b128 v[236:239], v201 offset:20032
	ds_read_b128 v[240:243], v201 offset:20096
	ds_read_b128 v[244:247], v201 offset:23296
	ds_read_b128 v[142:145], v201 offset:23360
	ds_read_b128 v[146:149], v201 offset:23424
	s_waitcnt lgkmcnt(11)
	v_mfma_f32_16x16x32_bf16 v[78:81], v[164:167], v[2:5], 0
	s_waitcnt lgkmcnt(10)
	v_mfma_f32_16x16x32_bf16 v[78:81], v[168:171], v[6:9], v[78:81]
	s_waitcnt lgkmcnt(9)
	v_mfma_f32_16x16x32_bf16 v[78:81], v[172:175], v[38:41], v[78:81]
	s_waitcnt lgkmcnt(8)
	v_mfma_f32_16x16x32_bf16 v[82:85], v[176:179], v[2:5], 0
	s_waitcnt lgkmcnt(7)
	v_mfma_f32_16x16x32_bf16 v[82:85], v[180:183], v[6:9], v[82:85]
	s_waitcnt lgkmcnt(6)
	v_mfma_f32_16x16x32_bf16 v[82:85], v[184:187], v[38:41], v[82:85]
	s_waitcnt lgkmcnt(5)
	v_mfma_f32_16x16x32_bf16 v[86:89], v[232:235], v[2:5], 0
	s_waitcnt lgkmcnt(4)
	v_mfma_f32_16x16x32_bf16 v[86:89], v[236:239], v[6:9], v[86:89]
	s_waitcnt lgkmcnt(3)
	v_mfma_f32_16x16x32_bf16 v[86:89], v[240:243], v[38:41], v[86:89]
	s_waitcnt lgkmcnt(2)
	v_mfma_f32_16x16x32_bf16 v[90:93], v[244:247], v[2:5], 0
	s_waitcnt lgkmcnt(1)
	v_mfma_f32_16x16x32_bf16 v[90:93], v[142:145], v[6:9], v[90:93]
	s_waitcnt lgkmcnt(0)
	v_mfma_f32_16x16x32_bf16 v[90:93], v[146:149], v[38:41], v[90:93]
	v_mfma_f32_16x16x32_bf16 v[94:97], v[164:167], v[26:29], 0
	v_max3_f32 v150, v78, s18, v79
	v_max3_f32 v150, v150, v80, v81
	v_max3_f32 v150, v150, v82, v83
	v_max3_f32 v150, v150, v84, v85
	v_max3_f32 v150, v150, v86, v87
	v_max3_f32 v150, v150, v88, v89
	s_nop 0
	v_max3_f32 v150, v150, v90, v91
	v_mfma_f32_16x16x32_bf16 v[94:97], v[168:171], v[30:33], v[94:97]
	v_max3_f32 v150, v150, v92, v93
	v_mul_f32_e32 v150, 0x3e16c740, v150
	v_mov_b32_e32 v152, v150
	s_nop 1
	v_permlane16_swap_b32_e32 v152, v150
	v_max_f32_e32 v150, v150, v152
	v_mov_b32_e32 v152, v150
	s_nop 1
	v_permlane32_swap_b32_e32 v152, v150
	v_mfma_f32_16x16x32_bf16 v[94:97], v[172:175], v[42:45], v[94:97]
	v_max_f32_e32 v150, v150, v152
	v_add_f32_e32 v154, 0x41000000, v139
	v_cmp_gt_f32_e32 vcc, v150, v154
	s_cbranch_vccz .Lmla_s1_keep0
	v_max_f32_e32 v158, v139, v150
	v_sub_f32_e32 v154, v139, v158
	v_exp_f32_e32 v154, v154
	v_mov_b32_e32 v139, v158
	v_mul_f32_e32 v141, v141, v154
	v_pk_mul_f32 v[74:75], v[74:75], v[154:155] op_sel_hi:[1,0]
	v_pk_mul_f32 v[76:77], v[76:77], v[154:155] op_sel_hi:[1,0]
	v_pk_mul_f32 v[70:71], v[70:71], v[154:155] op_sel_hi:[1,0]
	v_pk_mul_f32 v[72:73], v[72:73], v[154:155] op_sel_hi:[1,0]
	v_pk_mul_f32 v[66:67], v[66:67], v[154:155] op_sel_hi:[1,0]
	v_pk_mul_f32 v[68:69], v[68:69], v[154:155] op_sel_hi:[1,0]
	v_pk_mul_f32 v[62:63], v[62:63], v[154:155] op_sel_hi:[1,0]
	v_pk_mul_f32 v[64:65], v[64:65], v[154:155] op_sel_hi:[1,0]

.Lmla_s1_keep1:
	v_fma_f32 v94, v94, s21, -v138
	v_fma_f32 v95, v95, s21, -v138
	v_exp_f32_e32 v94, v94
	v_fma_f32 v96, v96, s21, -v138
	v_exp_f32_e32 v95, v95
	v_fma_f32 v97, v97, s21, -v138
	v_exp_f32_e32 v96, v96
	s_waitcnt lgkmcnt(12)
	v_mfma_f32_16x16x32_bf16 v[70:73], v[168:171], v[78:81], v[70:73]
	v_exp_f32_e32 v97, v97
	v_fma_f32 v98, v98, s21, -v138
	v_fma_f32 v99, v99, s21, -v138
	v_exp_f32_e32 v98, v98
	v_fma_f32 v100, v100, s21, -v138
	v_exp_f32_e32 v99, v99
	v_fma_f32 v101, v101, s21, -v138
	v_exp_f32_e32 v100, v100
	s_waitcnt lgkmcnt(10)
	v_mfma_f32_16x16x32_bf16 v[74:77], v[172:175], v[82:85], v[74:77]
	v_exp_f32_e32 v101, v101
	v_add_f32_e32 v161, 0, v94
	v_add_f32_e32 v161, v95, v161
	v_add_f32_e32 v161, v96, v161
	v_add_f32_e32 v161, v97, v161
	v_cvt_pk_bf16_f32 v94, v94, v95
	v_cvt_pk_bf16_f32 v95, v96, v97
	v_fma_f32 v102, v102, s21, -v138
	s_waitcnt lgkmcnt(8)
	v_mfma_f32_16x16x32_bf16 v[70:73], v[176:179], v[82:85], v[70:73]
	v_fma_f32 v103, v103, s21, -v138
	v_exp_f32_e32 v102, v102
	v_fma_f32 v104, v104, s21, -v138
	v_exp_f32_e32 v103, v103
	v_fma_f32 v105, v105, s21, -v138
	v_exp_f32_e32 v104, v104
	v_exp_f32_e32 v105, v105
	v_add_f32_e32 v161, v98, v161
	s_waitcnt lgkmcnt(6)
	v_mfma_f32_16x16x32_bf16 v[66:69], v[232:235], v[78:81], v[66:69]
	v_add_f32_e32 v161, v99, v161
	v_add_f32_e32 v161, v100, v161
	v_add_f32_e32 v161, v101, v161
	v_cvt_pk_bf16_f32 v96, v98, v99
	v_cvt_pk_bf16_f32 v97, v100, v101
	v_fma_f32 v106, v106, s21, -v138
	v_fma_f32 v107, v107, s21, -v138
	v_exp_f32_e32 v106, v106
	s_waitcnt lgkmcnt(4)
	v_mfma_f32_16x16x32_bf16 v[62:65], v[236:239], v[78:81], v[62:65]
	v_fma_f32 v108, v108, s21, -v138
	v_exp_f32_e32 v107, v107
	v_fma_f32 v109, v109, s21, -v138
	v_exp_f32_e32 v108, v108
	v_exp_f32_e32 v109, v109
	v_add_f32_e32 v161, v102, v161
	v_add_f32_e32 v161, v103, v161
	v_add_f32_e32 v161, v104, v161
	s_waitcnt lgkmcnt(2)
	v_mfma_f32_16x16x32_bf16 v[66:69], v[240:243], v[82:85], v[66:69]
	v_add_f32_e32 v161, v105, v161
	v_cvt_pk_bf16_f32 v98, v102, v103
	v_cvt_pk_bf16_f32 v99, v104, v105
	v_add_f32_e32 v161, v106, v161
	v_add_f32_e32 v161, v107, v161
	v_add_f32_e32 v161, v108, v161
	v_add_f32_e32 v161, v109, v161
	v_cvt_pk_bf16_f32 v100, v106, v107
	s_waitcnt lgkmcnt(0)
	v_mfma_f32_16x16x32_bf16 v[62:65], v[244:247], v[82:85], v[62:65]
	v_cvt_pk_bf16_f32 v101, v108, v109
	v_add_f32_e32 v140, v140, v161
	v_mfma_f32_16x16x32_bf16 v[58:61], v[164:167], v[94:97], v[58:61]
	v_mfma_f32_16x16x32_bf16 v[54:57], v[168:171], v[94:97], v[54:57]
	v_mfma_f32_16x16x32_bf16 v[58:61], v[172:175], v[98:101], v[58:61]
	v_mfma_f32_16x16x32_bf16 v[54:57], v[176:179], v[98:101], v[54:57]
	v_mfma_f32_16x16x32_bf16 v[50:53], v[232:235], v[94:97], v[50:53]
	v_mfma_f32_16x16x32_bf16 v[46:49], v[236:239], v[94:97], v[46:49]
	v_mfma_f32_16x16x32_bf16 v[50:53], v[240:243], v[98:101], v[50:53]
	v_mfma_f32_16x16x32_bf16 v[46:49], v[244:247], v[98:101], v[46:49]
	s_andn2_b64 vcc, exec, s[2:3]
	s_cbranch_vccnz .LBB0_556
	s_xor_b32 s5, s5, 0x80
	s_cmp_eq_u32 s5, 0
	s_cbranch_scc1 .Lmla_stage_buf0
	s_waitcnt vmcnt(4)
	ds_write_b128 v224, v[10:13] offset:26624
	s_waitcnt vmcnt(3)
	ds_write_b128 v229, v[14:17] offset:53248
	s_waitcnt vmcnt(2)
	ds_write_b128 v226, v[18:21] offset:26624
	s_waitcnt vmcnt(1)
	ds_write_b128 v230, v[22:25] offset:53248
	s_waitcnt vmcnt(0)
	ds_write_b128 v228, v[34:37] offset:26752
	s_branch .LBB0_556
